# v19 + phase-10 epilogue: row sums and shift quads loaded once per tile, per-step reload waits removed
# speedup vs baseline: 1.0073x; 1.0073x over previous
; __device__ __forceinline__ unsigned cvt_pk_bf16(float lo, float hi) { unsigned r; asm volatile("v_cvt_pk_bf16_f32 %0, %1, %2" : "=v"(r) : "v"(lo), "v"(hi)); return r; }
;     __device__ __forceinline__ void operator()(const gacc_t (&acc)[2][2][4][2], const Unit& u, int wr, int wc, int fr, int fq) const {
;         const int row0 = u.pm * 256 + wr * 64 + fr, col0 = u.pn * 256 + wc * 32 + 8 * fq;
;         const int ra = row_off + u.pm * 256; const float* shp = shw + (ra < ML ? (ra >> 11) : 8) * ldshw + col_off + col0;
; #pragma unroll
;         for (int ai = 0; ai < 2; ++ai)
; #pragma unroll
;             for (int m = 0; m < 4; ++m) { bf16_t* rowp = O + (size_t)(row0 + ai * 128 + m * 16) * ldc + col0;
;                 float rs = 1.f; if (ss) rs = 1.0f / sqrtf(ss[row_off + row0 + ai * 128 + m * 16] * (1.0f / D) + NEPS);
; #pragma unroll
;                 for (int bj = 0; bj < 2; ++bj) { gacc_t v0 = acc[ai][bj][m][0], v1 = acc[ai][bj][m][1]; u32x4 w;
;                     if (ss) { const f32x4 s0 = *(const f32x4*)(shp + bj * 128), s1 = *(const f32x4*)(shp + bj * 128 + 4);
;                         v0[0] = v0[0] * rs + s0.x; v0[1] = v0[1] * rs + s0.y; v0[2] = v0[2] * rs + s0.z; v0[3] = v0[3] * rs + s0.w; v1[0] = v1[0] * rs + s1.x; v1[1] = v1[1] * rs + s1.y; v1[2] = v1[2] * rs + s1.z; v1[3] = v1[3] * rs + s1.w; }
;                     w.x = pg8::cvt_pk_bf16(v0[0], v0[1]); w.y = pg8::cvt_pk_bf16(v0[2], v0[3]); w.z = pg8::cvt_pk_bf16(v1[0], v1[1]); w.w = pg8::cvt_pk_bf16(v1[2], v1[3]);
;                     *(u32x4*)(rowp + bj * 128) = w; } }
.LBB0_956:
	s_lshl_b32 s0, s0, 8
	v_add_u32_e32 v144, s0, v155
	v_add_u32_e32 v142, s72, v144
	v_ashrrev_i32_e32 v143, 31, v142
	v_lshl_add_u64 v[142:143], v[142:143], 2, s[4:5]
	global_load_dword v159, v[142:143], off
	global_load_dword v231, v[142:143], off offset:64
	global_load_dword v232, v[142:143], off offset:128
	global_load_dword v233, v[142:143], off offset:192
	global_load_dword v234, v[142:143], off offset:512
	global_load_dword v235, v[142:143], off offset:576
	global_load_dword v236, v[142:143], off offset:640
	global_load_dword v237, v[142:143], off offset:704
	s_add_i32 s0, s0, s72
	s_min_i32 s0, s0, 0x4000
	s_lshl_b32 s0, s0, 1
	s_and_b32 s0, s0, 0xfffff000
	v_lshl_or_b32 v146, s1, 8, v157
	s_ashr_i32 s1, s0, 31
	s_lshl_b64 s[0:1], s[0:1], 2
	s_add_u32 s0, s76, s0
	v_ashrrev_i32_e32 v147, 31, v146
	s_addc_u32 s1, s77, s1
	v_lshl_add_u64 v[142:143], v[146:147], 2, s[0:1]
	global_load_dwordx4 v[160:163], v[142:143], off
	global_load_dwordx4 v[164:167], v[142:143], off offset:16
	global_load_dwordx4 v[238:241], v[142:143], off
	global_load_dwordx4 v[242:245], v[142:143], off offset:16
	global_load_dwordx4 v[246:249], v[142:143], off offset:512
	global_load_dwordx4 v[250:253], v[142:143], off offset:528
	v_ashrrev_i32_e32 v145, 31, v144
	v_lshlrev_b64 v[146:147], 1, v[146:147]
	s_waitcnt vmcnt(0)
	v_fmamk_f32 v159, v159, 0x3a000000, v153
	v_mul_f32_e32 v168, 0x4f800000, v159
	v_cmp_gt_f32_e32 vcc, s58, v159
	s_nop 1
	v_cndmask_b32_e32 v159, v159, v168, vcc
	v_sqrt_f32_e32 v170, v159
	v_lshlrev_b64 v[168:169], s93, v[144:145]
	v_lshl_add_u64 v[168:169], v[168:169], 1, s[24:25]
	v_lshl_add_u64 v[168:169], v[168:169], 0, v[146:147]
	v_add_u32_e32 v145, -1, v170
	v_add_u32_e32 v171, 1, v170
	v_fma_f32 v172, -v145, v170, v159
	v_fma_f32 v173, -v171, v170, v159
	v_cmp_ge_f32_e64 s[0:1], 0, v172
	s_nop 1
	v_cndmask_b32_e64 v145, v170, v145, s[0:1]
	v_cmp_lt_f32_e64 s[0:1], 0, v173
	s_nop 1
	v_cndmask_b32_e64 v145, v145, v171, s[0:1]
	v_mul_f32_e32 v170, 0x37800000, v145
	v_cndmask_b32_e32 v145, v145, v170, vcc
	v_cmp_class_f32_e32 vcc, v159, v154
	s_nop 1
	v_cndmask_b32_e32 v145, v145, v159, vcc
	v_div_scale_f32 v159, s[0:1], v145, v145, 1.0
	v_rcp_f32_e32 v170, v159
	v_div_scale_f32 v171, vcc, 1.0, v145, 1.0
	v_fma_f32 v172, -v159, v170, 1.0
	v_fmac_f32_e32 v170, v172, v170
	v_mul_f32_e32 v172, v171, v170
	v_fma_f32 v173, -v159, v172, v171
	v_fmac_f32_e32 v172, v173, v170
	v_fma_f32 v159, -v159, v172, v171
	v_div_fmas_f32 v159, v159, v170, v172
	v_div_fixup_f32 v145, v159, v145, 1.0
	v_fma_f32 v124, v124, v145, v160
	v_fma_f32 v125, v125, v145, v161
	v_fma_f32 v126, v126, v145, v162
	v_fmac_f32_e32 v163, v127, v145
	v_fma_f32 v127, v120, v145, v164
	v_fma_f32 v159, v121, v145, v165
	v_fma_f32 v160, v122, v145, v166
	v_fmac_f32_e32 v167, v123, v145
	v_cvt_pk_bf16_f32 v120, v124, v125
	v_cvt_pk_bf16_f32 v121, v126, v163
	v_cvt_pk_bf16_f32 v122, v127, v159
	v_cvt_pk_bf16_f32 v123, v160, v167
	global_store_dwordx4 v[168:169], v[120:123], off
	s_nop 1
	v_mov_b64_e32 v[120:121], v[246:247]
	v_mov_b64_e32 v[122:123], v[248:249]
	s_nop 0
	v_mov_b64_e32 v[124:125], v[250:251]
	v_mov_b64_e32 v[126:127], v[252:253]
	v_or_b32_e32 v160, 16, v144
	v_add_u32_e32 v162, s72, v160
	v_ashrrev_i32_e32 v163, 31, v162
	v_lshl_add_u64 v[162:163], v[162:163], 2, s[4:5]
	v_ashrrev_i32_e32 v161, 31, v160
	v_fma_f32 v116, v116, v145, v120
	v_fma_f32 v117, v117, v145, v121
	v_fma_f32 v118, v118, v145, v122
	v_fmac_f32_e32 v123, v119, v145
	v_fma_f32 v119, v112, v145, v124
	v_fma_f32 v120, v113, v145, v125
	v_fma_f32 v121, v114, v145, v126
	v_fmac_f32_e32 v127, v115, v145
	v_cvt_pk_bf16_f32 v112, v116, v117
	v_cvt_pk_bf16_f32 v113, v118, v123
	v_cvt_pk_bf16_f32 v114, v119, v120
	v_cvt_pk_bf16_f32 v115, v121, v127
	global_store_dwordx4 v[168:169], v[112:115], off offset:256
	s_nop 1
	v_mov_b32_e32 v120, v231
	s_nop 0
	v_mov_b64_e32 v[112:113], v[238:239]
	v_mov_b64_e32 v[114:115], v[240:241]
	v_mov_b64_e32 v[116:117], v[242:243]
	v_mov_b64_e32 v[118:119], v[244:245]
	v_fmamk_f32 v120, v120, 0x3a000000, v153
	v_mul_f32_e32 v121, 0x4f800000, v120
	v_cmp_gt_f32_e32 vcc, s58, v120
	s_nop 1
	v_cndmask_b32_e32 v122, v120, v121, vcc
	v_sqrt_f32_e32 v123, v122
	v_lshlrev_b64 v[120:121], s93, v[160:161]
	v_lshl_add_u64 v[120:121], v[120:121], 1, s[24:25]
	v_lshl_add_u64 v[120:121], v[120:121], 0, v[146:147]
	v_add_u32_e32 v124, -1, v123
	v_add_u32_e32 v125, 1, v123
	v_fma_f32 v126, -v124, v123, v122
	v_fma_f32 v127, -v125, v123, v122
	v_cmp_ge_f32_e64 s[0:1], 0, v126
	s_nop 1
	v_cndmask_b32_e64 v123, v123, v124, s[0:1]
	v_cmp_lt_f32_e64 s[0:1], 0, v127
	s_nop 1
	v_cndmask_b32_e64 v123, v123, v125, s[0:1]
	v_mul_f32_e32 v124, 0x37800000, v123
	v_cndmask_b32_e32 v123, v123, v124, vcc
	v_cmp_class_f32_e32 vcc, v122, v154
	s_nop 1
	v_cndmask_b32_e32 v122, v123, v122, vcc
	v_div_scale_f32 v123, s[0:1], v122, v122, 1.0
	v_rcp_f32_e32 v124, v123
	v_div_scale_f32 v125, vcc, 1.0, v122, 1.0
	v_fma_f32 v126, -v123, v124, 1.0
	v_fmac_f32_e32 v124, v126, v124
	v_mul_f32_e32 v126, v125, v124
	v_fma_f32 v127, -v123, v126, v125
	v_fmac_f32_e32 v126, v127, v124
	v_fma_f32 v123, -v123, v126, v125
	v_div_fmas_f32 v123, v123, v124, v126
	v_div_fixup_f32 v122, v123, v122, 1.0
	v_fma_f32 v108, v108, v122, v112
	v_fma_f32 v109, v109, v122, v113
	v_fma_f32 v110, v110, v122, v114
	v_fmac_f32_e32 v115, v111, v122
	v_fma_f32 v111, v104, v122, v116
	v_fma_f32 v112, v105, v122, v117
	v_fma_f32 v113, v106, v122, v118
	v_fmac_f32_e32 v119, v107, v122
	v_cvt_pk_bf16_f32 v104, v108, v109
	v_cvt_pk_bf16_f32 v105, v110, v115
	v_cvt_pk_bf16_f32 v106, v111, v112
	v_cvt_pk_bf16_f32 v107, v113, v119
; __device__ __forceinline__ unsigned cvt_pk_bf16(float lo, float hi) { unsigned r; asm volatile("v_cvt_pk_bf16_f32 %0, %1, %2" : "=v"(r) : "v"(lo), "v"(hi)); return r; }
;     __device__ __forceinline__ void operator()(const gacc_t (&acc)[2][2][4][2], const Unit& u, int wr, int wc, int fr, int fq) const {
;     ...
;             for (int m = 0; m < 4; ++m) { bf16_t* rowp = O + (size_t)(row0 + ai * 128 + m * 16) * ldc + col0;
;                 float rs = 1.f; if (ss) rs = 1.0f / sqrtf(ss[row_off + row0 + ai * 128 + m * 16] * (1.0f / D) + NEPS);
; #pragma unroll
;                 for (int bj = 0; bj < 2; ++bj) { gacc_t v0 = acc[ai][bj][m][0], v1 = acc[ai][bj][m][1]; u32x4 w;
;                     if (ss) { const f32x4 s0 = *(const f32x4*)(shp + bj * 128), s1 = *(const f32x4*)(shp + bj * 128 + 4);
;                         v0[0] = v0[0] * rs + s0.x; v0[1] = v0[1] * rs + s0.y; v0[2] = v0[2] * rs + s0.z; v0[3] = v0[3] * rs + s0.w; v1[0] = v1[0] * rs + s1.x; v1[1] = v1[1] * rs + s1.y; v1[2] = v1[2] * rs + s1.z; v1[3] = v1[3] * rs + s1.w; }
;                     w.x = pg8::cvt_pk_bf16(v0[0], v0[1]); w.y = pg8::cvt_pk_bf16(v0[2], v0[3]); w.z = pg8::cvt_pk_bf16(v1[0], v1[1]); w.w = pg8::cvt_pk_bf16(v1[2], v1[3]);
;                     *(u32x4*)(rowp + bj * 128) = w; } }
	global_store_dwordx4 v[120:121], v[104:107], off
	s_nop 1
	v_mov_b64_e32 v[104:105], v[246:247]
	v_mov_b64_e32 v[106:107], v[248:249]
	s_nop 0
	v_mov_b64_e32 v[108:109], v[250:251]
	v_mov_b64_e32 v[110:111], v[252:253]
	v_or_b32_e32 v112, 32, v144
	v_add_u32_e32 v114, s72, v112
	v_ashrrev_i32_e32 v115, 31, v114
	v_lshl_add_u64 v[114:115], v[114:115], 2, s[4:5]
	v_ashrrev_i32_e32 v113, 31, v112
	v_fma_f32 v100, v100, v122, v104
	v_fma_f32 v101, v101, v122, v105
	v_fma_f32 v102, v102, v122, v106
	v_fmac_f32_e32 v107, v103, v122
	v_fma_f32 v103, v96, v122, v108
	v_fma_f32 v104, v97, v122, v109
	v_fma_f32 v105, v98, v122, v110
	v_fmac_f32_e32 v111, v99, v122
	v_cvt_pk_bf16_f32 v96, v100, v101
	v_cvt_pk_bf16_f32 v97, v102, v107
	v_cvt_pk_bf16_f32 v98, v103, v104
	v_cvt_pk_bf16_f32 v99, v105, v111
	global_store_dwordx4 v[120:121], v[96:99], off offset:256
	s_nop 1
	v_mov_b32_e32 v104, v232
	s_nop 0
	v_mov_b64_e32 v[96:97], v[238:239]
	v_mov_b64_e32 v[98:99], v[240:241]
	v_mov_b64_e32 v[100:101], v[242:243]
	v_mov_b64_e32 v[102:103], v[244:245]
	v_fmamk_f32 v104, v104, 0x3a000000, v153
	v_mul_f32_e32 v105, 0x4f800000, v104
	v_cmp_gt_f32_e32 vcc, s58, v104
	s_nop 1
	v_cndmask_b32_e32 v106, v104, v105, vcc
	v_sqrt_f32_e32 v107, v106
	v_lshlrev_b64 v[104:105], s93, v[112:113]
	v_lshl_add_u64 v[104:105], v[104:105], 1, s[24:25]
	v_lshl_add_u64 v[104:105], v[104:105], 0, v[146:147]
	v_add_u32_e32 v108, -1, v107
	v_add_u32_e32 v109, 1, v107
	v_fma_f32 v110, -v108, v107, v106
	v_fma_f32 v111, -v109, v107, v106
	v_cmp_ge_f32_e64 s[0:1], 0, v110
	s_nop 1
	v_cndmask_b32_e64 v107, v107, v108, s[0:1]
	v_cmp_lt_f32_e64 s[0:1], 0, v111
	s_nop 1
	v_cndmask_b32_e64 v107, v107, v109, s[0:1]
	v_mul_f32_e32 v108, 0x37800000, v107
	v_cndmask_b32_e32 v107, v107, v108, vcc
	v_cmp_class_f32_e32 vcc, v106, v154
	s_nop 1
	v_cndmask_b32_e32 v106, v107, v106, vcc
	v_div_scale_f32 v107, s[0:1], v106, v106, 1.0
	v_rcp_f32_e32 v108, v107
	v_div_scale_f32 v109, vcc, 1.0, v106, 1.0
	v_fma_f32 v110, -v107, v108, 1.0
	v_fmac_f32_e32 v108, v110, v108
	v_mul_f32_e32 v110, v109, v108
	v_fma_f32 v111, -v107, v110, v109
	v_fmac_f32_e32 v110, v111, v108
	v_fma_f32 v107, -v107, v110, v109
	v_div_fmas_f32 v107, v107, v108, v110
	v_div_fixup_f32 v106, v107, v106, 1.0
	v_fma_f32 v92, v92, v106, v96
	v_fma_f32 v93, v93, v106, v97
	v_fma_f32 v94, v94, v106, v98
	v_fmac_f32_e32 v99, v95, v106
	v_fma_f32 v95, v88, v106, v100
	v_fma_f32 v96, v89, v106, v101
	v_fma_f32 v97, v90, v106, v102
	v_fmac_f32_e32 v103, v91, v106
	v_cvt_pk_bf16_f32 v88, v92, v93
	v_cvt_pk_bf16_f32 v89, v94, v99
	v_cvt_pk_bf16_f32 v90, v95, v96
	v_cvt_pk_bf16_f32 v91, v97, v103
	global_store_dwordx4 v[104:105], v[88:91], off
	s_nop 1
	v_mov_b64_e32 v[88:89], v[246:247]
	v_mov_b64_e32 v[90:91], v[248:249]
	s_nop 0
	v_mov_b64_e32 v[92:93], v[250:251]
	v_mov_b64_e32 v[94:95], v[252:253]
	v_or_b32_e32 v96, 48, v144
	v_add_u32_e32 v98, s72, v96
	v_ashrrev_i32_e32 v99, 31, v98
	v_lshl_add_u64 v[98:99], v[98:99], 2, s[4:5]
	v_ashrrev_i32_e32 v97, 31, v96
	v_fma_f32 v84, v84, v106, v88
	v_fma_f32 v85, v85, v106, v89
	v_fma_f32 v86, v86, v106, v90
	v_fmac_f32_e32 v91, v87, v106
	v_fma_f32 v87, v80, v106, v92
	v_fma_f32 v88, v81, v106, v93
	v_fma_f32 v89, v82, v106, v94
	v_fmac_f32_e32 v95, v83, v106
	v_cvt_pk_bf16_f32 v80, v84, v85
	v_cvt_pk_bf16_f32 v81, v86, v91
	v_cvt_pk_bf16_f32 v82, v87, v88
	v_cvt_pk_bf16_f32 v83, v89, v95
	global_store_dwordx4 v[104:105], v[80:83], off offset:256
	s_nop 1
	v_mov_b32_e32 v88, v233
	s_nop 0
	v_mov_b64_e32 v[80:81], v[238:239]
	v_mov_b64_e32 v[82:83], v[240:241]
	v_mov_b64_e32 v[84:85], v[242:243]
	v_mov_b64_e32 v[86:87], v[244:245]
	v_fmamk_f32 v88, v88, 0x3a000000, v153
	v_mul_f32_e32 v89, 0x4f800000, v88
	v_cmp_gt_f32_e32 vcc, s58, v88
	s_nop 1
	v_cndmask_b32_e32 v90, v88, v89, vcc
	v_sqrt_f32_e32 v91, v90
	v_lshlrev_b64 v[88:89], s93, v[96:97]
	v_lshl_add_u64 v[88:89], v[88:89], 1, s[24:25]
	v_lshl_add_u64 v[88:89], v[88:89], 0, v[146:147]
	v_add_u32_e32 v92, -1, v91
	v_add_u32_e32 v93, 1, v91
	v_fma_f32 v94, -v92, v91, v90
	v_fma_f32 v95, -v93, v91, v90
	v_cmp_ge_f32_e64 s[0:1], 0, v94
	s_nop 1
	v_cndmask_b32_e64 v91, v91, v92, s[0:1]
	v_cmp_lt_f32_e64 s[0:1], 0, v95
	s_nop 1
	v_cndmask_b32_e64 v91, v91, v93, s[0:1]
	v_mul_f32_e32 v92, 0x37800000, v91
	v_cndmask_b32_e32 v91, v91, v92, vcc
	v_cmp_class_f32_e32 vcc, v90, v154
	s_nop 1
	v_cndmask_b32_e32 v90, v91, v90, vcc
	v_div_scale_f32 v91, s[0:1], v90, v90, 1.0
	v_rcp_f32_e32 v92, v91
	v_div_scale_f32 v93, vcc, 1.0, v90, 1.0
	v_fma_f32 v94, -v91, v92, 1.0
	v_fmac_f32_e32 v92, v94, v92
	v_mul_f32_e32 v94, v93, v92
	v_fma_f32 v95, -v91, v94, v93
	v_fmac_f32_e32 v94, v95, v92
	v_fma_f32 v91, -v91, v94, v93
	v_div_fmas_f32 v91, v91, v92, v94
	v_div_fixup_f32 v90, v91, v90, 1.0
	v_fma_f32 v76, v76, v90, v80
	v_fma_f32 v77, v77, v90, v81
	v_fma_f32 v78, v78, v90, v82
	v_fmac_f32_e32 v83, v79, v90
	v_fma_f32 v79, v72, v90, v84
	v_fma_f32 v80, v73, v90, v85
	v_fma_f32 v81, v74, v90, v86
	v_fmac_f32_e32 v87, v75, v90
	v_cvt_pk_bf16_f32 v72, v76, v77
	v_cvt_pk_bf16_f32 v73, v78, v83
	v_cvt_pk_bf16_f32 v74, v79, v80
	v_cvt_pk_bf16_f32 v75, v81, v87
	global_store_dwordx4 v[88:89], v[72:75], off
	s_nop 1
	v_mov_b64_e32 v[72:73], v[246:247]
	v_mov_b64_e32 v[74:75], v[248:249]
	s_nop 0
	v_mov_b64_e32 v[76:77], v[250:251]
	v_mov_b64_e32 v[78:79], v[252:253]
	v_add_u32_e32 v80, 0x80, v144
	v_add_u32_e32 v82, s72, v80
	v_ashrrev_i32_e32 v83, 31, v82
	v_lshl_add_u64 v[82:83], v[82:83], 2, s[4:5]
	v_ashrrev_i32_e32 v81, 31, v80
	v_fma_f32 v68, v68, v90, v72
	v_fma_f32 v69, v69, v90, v73
	v_fma_f32 v70, v70, v90, v74
	v_fmac_f32_e32 v75, v71, v90
; __device__ __forceinline__ unsigned cvt_pk_bf16(float lo, float hi) { unsigned r; asm volatile("v_cvt_pk_bf16_f32 %0, %1, %2" : "=v"(r) : "v"(lo), "v"(hi)); return r; }
;     __device__ __forceinline__ void operator()(const gacc_t (&acc)[2][2][4][2], const Unit& u, int wr, int wc, int fr, int fq) const {
;     ...
;             for (int m = 0; m < 4; ++m) { bf16_t* rowp = O + (size_t)(row0 + ai * 128 + m * 16) * ldc + col0;
;                 float rs = 1.f; if (ss) rs = 1.0f / sqrtf(ss[row_off + row0 + ai * 128 + m * 16] * (1.0f / D) + NEPS);
; #pragma unroll
;                 for (int bj = 0; bj < 2; ++bj) { gacc_t v0 = acc[ai][bj][m][0], v1 = acc[ai][bj][m][1]; u32x4 w;
;                     if (ss) { const f32x4 s0 = *(const f32x4*)(shp + bj * 128), s1 = *(const f32x4*)(shp + bj * 128 + 4);
;                         v0[0] = v0[0] * rs + s0.x; v0[1] = v0[1] * rs + s0.y; v0[2] = v0[2] * rs + s0.z; v0[3] = v0[3] * rs + s0.w; v1[0] = v1[0] * rs + s1.x; v1[1] = v1[1] * rs + s1.y; v1[2] = v1[2] * rs + s1.z; v1[3] = v1[3] * rs + s1.w; }
;                     w.x = pg8::cvt_pk_bf16(v0[0], v0[1]); w.y = pg8::cvt_pk_bf16(v0[2], v0[3]); w.z = pg8::cvt_pk_bf16(v1[0], v1[1]); w.w = pg8::cvt_pk_bf16(v1[2], v1[3]);
;                     *(u32x4*)(rowp + bj * 128) = w; } }
	v_fma_f32 v71, v64, v90, v76
	v_fma_f32 v72, v65, v90, v77
	v_fma_f32 v73, v66, v90, v78
	v_fmac_f32_e32 v79, v67, v90
	v_cvt_pk_bf16_f32 v64, v68, v69
	v_cvt_pk_bf16_f32 v65, v70, v75
	v_cvt_pk_bf16_f32 v66, v71, v72
	v_cvt_pk_bf16_f32 v67, v73, v79
	global_store_dwordx4 v[88:89], v[64:67], off offset:256
	s_nop 1
	v_mov_b32_e32 v72, v234
	s_nop 0
	v_mov_b64_e32 v[64:65], v[238:239]
	v_mov_b64_e32 v[66:67], v[240:241]
	v_mov_b64_e32 v[68:69], v[242:243]
	v_mov_b64_e32 v[70:71], v[244:245]
	v_fmamk_f32 v72, v72, 0x3a000000, v153
	v_mul_f32_e32 v73, 0x4f800000, v72
	v_cmp_gt_f32_e32 vcc, s58, v72
	s_nop 1
	v_cndmask_b32_e32 v74, v72, v73, vcc
	v_sqrt_f32_e32 v75, v74
	v_lshlrev_b64 v[72:73], s93, v[80:81]
	v_lshl_add_u64 v[72:73], v[72:73], 1, s[24:25]
	v_lshl_add_u64 v[72:73], v[72:73], 0, v[146:147]
	v_add_u32_e32 v76, -1, v75
	v_add_u32_e32 v77, 1, v75
	v_fma_f32 v78, -v76, v75, v74
	v_fma_f32 v79, -v77, v75, v74
	v_cmp_ge_f32_e64 s[0:1], 0, v78
	s_nop 1
	v_cndmask_b32_e64 v75, v75, v76, s[0:1]
	v_cmp_lt_f32_e64 s[0:1], 0, v79
	s_nop 1
	v_cndmask_b32_e64 v75, v75, v77, s[0:1]
	v_mul_f32_e32 v76, 0x37800000, v75
	v_cndmask_b32_e32 v75, v75, v76, vcc
	v_cmp_class_f32_e32 vcc, v74, v154
	s_nop 1
	v_cndmask_b32_e32 v74, v75, v74, vcc
	v_div_scale_f32 v75, s[0:1], v74, v74, 1.0
	v_rcp_f32_e32 v76, v75
	v_div_scale_f32 v77, vcc, 1.0, v74, 1.0
	v_fma_f32 v78, -v75, v76, 1.0
	v_fmac_f32_e32 v76, v78, v76
	v_mul_f32_e32 v78, v77, v76
	v_fma_f32 v79, -v75, v78, v77
	v_fmac_f32_e32 v78, v79, v76
	v_fma_f32 v75, -v75, v78, v77
	v_div_fmas_f32 v75, v75, v76, v78
	v_div_fixup_f32 v74, v75, v74, 1.0
	v_fma_f32 v60, v60, v74, v64
	v_fma_f32 v61, v61, v74, v65
	v_fma_f32 v62, v62, v74, v66
	v_fmac_f32_e32 v67, v63, v74
	v_fma_f32 v63, v56, v74, v68
	v_fma_f32 v64, v57, v74, v69
	v_fma_f32 v65, v58, v74, v70
	v_fmac_f32_e32 v71, v59, v74
	v_cvt_pk_bf16_f32 v56, v60, v61
	v_cvt_pk_bf16_f32 v57, v62, v67
	v_cvt_pk_bf16_f32 v58, v63, v64
	v_cvt_pk_bf16_f32 v59, v65, v71
	global_store_dwordx4 v[72:73], v[56:59], off
	s_nop 1
	v_mov_b64_e32 v[56:57], v[246:247]
	v_mov_b64_e32 v[58:59], v[248:249]
	s_nop 0
	v_mov_b64_e32 v[60:61], v[250:251]
	v_mov_b64_e32 v[62:63], v[252:253]
	v_add_u32_e32 v64, 0x90, v144
	v_add_u32_e32 v66, s72, v64
	v_ashrrev_i32_e32 v67, 31, v66
	v_lshl_add_u64 v[66:67], v[66:67], 2, s[4:5]
	v_ashrrev_i32_e32 v65, 31, v64
	v_fma_f32 v52, v52, v74, v56
	v_fma_f32 v53, v53, v74, v57
	v_fma_f32 v54, v54, v74, v58
	v_fmac_f32_e32 v59, v55, v74
	v_fma_f32 v55, v48, v74, v60
	v_fma_f32 v56, v49, v74, v61
	v_fma_f32 v57, v50, v74, v62
	v_fmac_f32_e32 v63, v51, v74
	v_cvt_pk_bf16_f32 v48, v52, v53
	v_cvt_pk_bf16_f32 v49, v54, v59
	v_cvt_pk_bf16_f32 v50, v55, v56
	v_cvt_pk_bf16_f32 v51, v57, v63
	global_store_dwordx4 v[72:73], v[48:51], off offset:256
	s_nop 1
	v_mov_b32_e32 v56, v235
	s_nop 0
	v_mov_b64_e32 v[48:49], v[238:239]
	v_mov_b64_e32 v[50:51], v[240:241]
	v_mov_b64_e32 v[52:53], v[242:243]
	v_mov_b64_e32 v[54:55], v[244:245]
	v_fmamk_f32 v56, v56, 0x3a000000, v153
	v_mul_f32_e32 v57, 0x4f800000, v56
	v_cmp_gt_f32_e32 vcc, s58, v56
	s_nop 1
	v_cndmask_b32_e32 v58, v56, v57, vcc
	v_sqrt_f32_e32 v59, v58
	v_lshlrev_b64 v[56:57], s93, v[64:65]
	v_lshl_add_u64 v[56:57], v[56:57], 1, s[24:25]
	v_lshl_add_u64 v[56:57], v[56:57], 0, v[146:147]
	v_add_u32_e32 v60, -1, v59
	v_add_u32_e32 v61, 1, v59
	v_fma_f32 v62, -v60, v59, v58
	v_fma_f32 v63, -v61, v59, v58
	v_cmp_ge_f32_e64 s[0:1], 0, v62
	s_nop 1
	v_cndmask_b32_e64 v59, v59, v60, s[0:1]
	v_cmp_lt_f32_e64 s[0:1], 0, v63
	s_nop 1
	v_cndmask_b32_e64 v59, v59, v61, s[0:1]
	v_mul_f32_e32 v60, 0x37800000, v59
	v_cndmask_b32_e32 v59, v59, v60, vcc
	v_cmp_class_f32_e32 vcc, v58, v154
	s_nop 1
	v_cndmask_b32_e32 v58, v59, v58, vcc
	v_div_scale_f32 v59, s[0:1], v58, v58, 1.0
	v_rcp_f32_e32 v60, v59
	v_div_scale_f32 v61, vcc, 1.0, v58, 1.0
	v_fma_f32 v62, -v59, v60, 1.0
	v_fmac_f32_e32 v60, v62, v60
	v_mul_f32_e32 v62, v61, v60
	v_fma_f32 v63, -v59, v62, v61
	v_fmac_f32_e32 v62, v63, v60
	v_fma_f32 v59, -v59, v62, v61
	v_div_fmas_f32 v59, v59, v60, v62
	v_div_fixup_f32 v58, v59, v58, 1.0
	v_fma_f32 v44, v44, v58, v48
	v_fma_f32 v45, v45, v58, v49
	v_fma_f32 v46, v46, v58, v50
	v_fmac_f32_e32 v51, v47, v58
	v_fma_f32 v47, v40, v58, v52
	v_fma_f32 v48, v41, v58, v53
	v_fma_f32 v49, v42, v58, v54
	v_fmac_f32_e32 v55, v43, v58
	v_cvt_pk_bf16_f32 v40, v44, v45
	v_cvt_pk_bf16_f32 v41, v46, v51
	v_cvt_pk_bf16_f32 v42, v47, v48
	v_cvt_pk_bf16_f32 v43, v49, v55
	global_store_dwordx4 v[56:57], v[40:43], off
	s_nop 1
	v_mov_b64_e32 v[40:41], v[246:247]
	v_mov_b64_e32 v[42:43], v[248:249]
	s_nop 0
	v_mov_b64_e32 v[44:45], v[250:251]
	v_mov_b64_e32 v[46:47], v[252:253]
	v_add_u32_e32 v48, 0xa0, v144
	v_add_u32_e32 v50, s72, v48
	v_ashrrev_i32_e32 v51, 31, v50
	v_lshl_add_u64 v[50:51], v[50:51], 2, s[4:5]
	v_ashrrev_i32_e32 v49, 31, v48
	v_fma_f32 v36, v36, v58, v40
	v_fma_f32 v37, v37, v58, v41
	v_fma_f32 v38, v38, v58, v42
	v_fmac_f32_e32 v43, v39, v58
	v_fma_f32 v39, v32, v58, v44
	v_fma_f32 v40, v33, v58, v45
	v_fma_f32 v41, v34, v58, v46
	v_fmac_f32_e32 v47, v35, v58
	v_cvt_pk_bf16_f32 v32, v36, v37
; __device__ __forceinline__ unsigned cvt_pk_bf16(float lo, float hi) { unsigned r; asm volatile("v_cvt_pk_bf16_f32 %0, %1, %2" : "=v"(r) : "v"(lo), "v"(hi)); return r; }
;     __device__ __forceinline__ void operator()(const gacc_t (&acc)[2][2][4][2], const Unit& u, int wr, int wc, int fr, int fq) const {
;     ...
;             for (int m = 0; m < 4; ++m) { bf16_t* rowp = O + (size_t)(row0 + ai * 128 + m * 16) * ldc + col0;
;                 float rs = 1.f; if (ss) rs = 1.0f / sqrtf(ss[row_off + row0 + ai * 128 + m * 16] * (1.0f / D) + NEPS);
; #pragma unroll
;                 for (int bj = 0; bj < 2; ++bj) { gacc_t v0 = acc[ai][bj][m][0], v1 = acc[ai][bj][m][1]; u32x4 w;
;                     if (ss) { const f32x4 s0 = *(const f32x4*)(shp + bj * 128), s1 = *(const f32x4*)(shp + bj * 128 + 4);
;                         v0[0] = v0[0] * rs + s0.x; v0[1] = v0[1] * rs + s0.y; v0[2] = v0[2] * rs + s0.z; v0[3] = v0[3] * rs + s0.w; v1[0] = v1[0] * rs + s1.x; v1[1] = v1[1] * rs + s1.y; v1[2] = v1[2] * rs + s1.z; v1[3] = v1[3] * rs + s1.w; }
;                     w.x = pg8::cvt_pk_bf16(v0[0], v0[1]); w.y = pg8::cvt_pk_bf16(v0[2], v0[3]); w.z = pg8::cvt_pk_bf16(v1[0], v1[1]); w.w = pg8::cvt_pk_bf16(v1[2], v1[3]);
;                     *(u32x4*)(rowp + bj * 128) = w; } }
	v_cvt_pk_bf16_f32 v33, v38, v43
	v_cvt_pk_bf16_f32 v34, v39, v40
	v_cvt_pk_bf16_f32 v35, v41, v47
	global_store_dwordx4 v[56:57], v[32:35], off offset:256
	s_nop 1
	v_mov_b32_e32 v40, v236
	s_nop 0
	v_mov_b64_e32 v[32:33], v[238:239]
	v_mov_b64_e32 v[34:35], v[240:241]
	v_mov_b64_e32 v[36:37], v[242:243]
	v_mov_b64_e32 v[38:39], v[244:245]
	v_fmamk_f32 v40, v40, 0x3a000000, v153
	v_mul_f32_e32 v41, 0x4f800000, v40
	v_cmp_gt_f32_e32 vcc, s58, v40
	s_nop 1
	v_cndmask_b32_e32 v42, v40, v41, vcc
	v_sqrt_f32_e32 v43, v42
	v_lshlrev_b64 v[40:41], s93, v[48:49]
	v_lshl_add_u64 v[40:41], v[40:41], 1, s[24:25]
	v_lshl_add_u64 v[40:41], v[40:41], 0, v[146:147]
	v_add_u32_e32 v44, -1, v43
	v_add_u32_e32 v45, 1, v43
	v_fma_f32 v46, -v44, v43, v42
	v_fma_f32 v47, -v45, v43, v42
	v_cmp_ge_f32_e64 s[0:1], 0, v46
	s_nop 1
	v_cndmask_b32_e64 v43, v43, v44, s[0:1]
	v_cmp_lt_f32_e64 s[0:1], 0, v47
	s_nop 1
	v_cndmask_b32_e64 v43, v43, v45, s[0:1]
	v_mul_f32_e32 v44, 0x37800000, v43
	v_cndmask_b32_e32 v43, v43, v44, vcc
	v_cmp_class_f32_e32 vcc, v42, v154
	s_nop 1
	v_cndmask_b32_e32 v42, v43, v42, vcc
	v_div_scale_f32 v43, s[0:1], v42, v42, 1.0
	v_rcp_f32_e32 v44, v43
	v_div_scale_f32 v45, vcc, 1.0, v42, 1.0
	v_fma_f32 v46, -v43, v44, 1.0
	v_fmac_f32_e32 v44, v46, v44
	v_mul_f32_e32 v46, v45, v44
	v_fma_f32 v47, -v43, v46, v45
	v_fmac_f32_e32 v46, v47, v44
	v_fma_f32 v43, -v43, v46, v45
	v_div_fmas_f32 v43, v43, v44, v46
	v_div_fixup_f32 v42, v43, v42, 1.0
	v_fma_f32 v28, v28, v42, v32
	v_fma_f32 v29, v29, v42, v33
	v_fma_f32 v30, v30, v42, v34
	v_fmac_f32_e32 v35, v31, v42
	v_fma_f32 v31, v24, v42, v36
	v_fma_f32 v32, v25, v42, v37
	v_fma_f32 v33, v26, v42, v38
	v_fmac_f32_e32 v39, v27, v42
	v_cvt_pk_bf16_f32 v24, v28, v29
	v_cvt_pk_bf16_f32 v25, v30, v35
	v_cvt_pk_bf16_f32 v26, v31, v32
	v_cvt_pk_bf16_f32 v27, v33, v39
	global_store_dwordx4 v[40:41], v[24:27], off
	s_nop 1
	v_mov_b64_e32 v[24:25], v[246:247]
	v_mov_b64_e32 v[26:27], v[248:249]
	s_nop 0
	v_mov_b64_e32 v[28:29], v[250:251]
	v_mov_b64_e32 v[30:31], v[252:253]
	v_add_u32_e32 v32, 0xb0, v144
	v_add_u32_e32 v34, s72, v32
	v_ashrrev_i32_e32 v35, 31, v34
	v_lshl_add_u64 v[34:35], v[34:35], 2, s[4:5]
	v_ashrrev_i32_e32 v33, 31, v32
	v_fma_f32 v20, v20, v42, v24
	v_fma_f32 v21, v21, v42, v25
	v_fma_f32 v22, v22, v42, v26
	v_fmac_f32_e32 v27, v23, v42
	v_fma_f32 v23, v16, v42, v28
	v_fma_f32 v24, v17, v42, v29
	v_fma_f32 v25, v18, v42, v30
	v_fmac_f32_e32 v31, v19, v42
	v_cvt_pk_bf16_f32 v16, v20, v21
	v_cvt_pk_bf16_f32 v17, v22, v27
	v_cvt_pk_bf16_f32 v18, v23, v24
	v_cvt_pk_bf16_f32 v19, v25, v31
	global_store_dwordx4 v[40:41], v[16:19], off offset:256
	s_nop 1
	v_mov_b32_e32 v24, v237
	s_nop 0
	v_mov_b64_e32 v[16:17], v[238:239]
	v_mov_b64_e32 v[18:19], v[240:241]
	v_mov_b64_e32 v[20:21], v[242:243]
	v_mov_b64_e32 v[22:23], v[244:245]
	v_fmamk_f32 v24, v24, 0x3a000000, v153
	v_mul_f32_e32 v25, 0x4f800000, v24
	v_cmp_gt_f32_e32 vcc, s58, v24
	s_nop 1
	v_cndmask_b32_e32 v26, v24, v25, vcc
	v_sqrt_f32_e32 v27, v26
	v_lshlrev_b64 v[24:25], s93, v[32:33]
	v_lshl_add_u64 v[24:25], v[24:25], 1, s[24:25]
	v_lshl_add_u64 v[24:25], v[24:25], 0, v[146:147]
	v_add_u32_e32 v28, -1, v27
	v_add_u32_e32 v29, 1, v27
	v_fma_f32 v30, -v28, v27, v26
	v_fma_f32 v31, -v29, v27, v26
	v_cmp_ge_f32_e64 s[0:1], 0, v30
	s_nop 1
	v_cndmask_b32_e64 v27, v27, v28, s[0:1]
	v_cmp_lt_f32_e64 s[0:1], 0, v31
	s_nop 1
	v_cndmask_b32_e64 v27, v27, v29, s[0:1]
	v_mul_f32_e32 v28, 0x37800000, v27
	v_cndmask_b32_e32 v27, v27, v28, vcc
	v_cmp_class_f32_e32 vcc, v26, v154
	s_nop 1
	v_cndmask_b32_e32 v26, v27, v26, vcc
	v_div_scale_f32 v27, s[0:1], v26, v26, 1.0
	v_rcp_f32_e32 v28, v27
	v_div_scale_f32 v29, vcc, 1.0, v26, 1.0
	s_mov_b64 s[0:1], -1
	v_fma_f32 v30, -v27, v28, 1.0
	v_fmac_f32_e32 v28, v30, v28
	v_mul_f32_e32 v30, v29, v28
	v_fma_f32 v31, -v27, v30, v29
	v_fmac_f32_e32 v30, v31, v28
	v_fma_f32 v27, -v27, v30, v29
	v_div_fmas_f32 v27, v27, v28, v30
	v_div_fixup_f32 v26, v27, v26, 1.0
	v_fma_f32 v12, v12, v26, v16
	v_fma_f32 v13, v13, v26, v17
	v_fma_f32 v14, v14, v26, v18
	v_fmac_f32_e32 v19, v15, v26
	v_fma_f32 v15, v8, v26, v20
	v_fma_f32 v16, v9, v26, v21
	v_fma_f32 v17, v10, v26, v22
	v_fmac_f32_e32 v23, v11, v26
	v_cvt_pk_bf16_f32 v8, v12, v13
	v_cvt_pk_bf16_f32 v9, v14, v19
	v_cvt_pk_bf16_f32 v10, v15, v16
	v_cvt_pk_bf16_f32 v11, v17, v23
	global_store_dwordx4 v[24:25], v[8:11], off
	s_nop 1
	v_mov_b64_e32 v[8:9], v[246:247]
	v_mov_b64_e32 v[10:11], v[248:249]
	s_nop 0
	v_mov_b64_e32 v[12:13], v[250:251]
	v_mov_b64_e32 v[14:15], v[252:253]
	s_andn2_b64 vcc, exec, s[2:3]
	v_fma_f32 v4, v4, v26, v8
	v_fma_f32 v5, v5, v26, v9
	v_fma_f32 v6, v6, v26, v10
	v_fmac_f32_e32 v11, v7, v26
	v_fma_f32 v7, v0, v26, v12
	v_fma_f32 v8, v1, v26, v13
	v_fma_f32 v9, v2, v26, v14
	v_fmac_f32_e32 v15, v3, v26
	v_cvt_pk_bf16_f32 v0, v4, v5
	v_cvt_pk_bf16_f32 v1, v6, v11
	v_cvt_pk_bf16_f32 v2, v7, v8
	v_cvt_pk_bf16_f32 v3, v9, v15
	global_store_dwordx4 v[24:25], v[0:3], off offset:256
	s_cbranch_vccnz .LBB0_949
	s_andn2_b64 vcc, exec, s[22:23]
	s_cbranch_vccnz .LBB0_948
	s_barrier
	s_branch .LBB0_948
